# A-layer LoRA-input prep phase rewritten: all 16 tokens of a wave loaded up front (32 loads in flight) instead of four serial rounds
# speedup vs baseline: 1.0041x; 1.0027x over previous
.LBB0_281:
	s_and_b64 vcc, exec, s[4:5]
	s_cbranch_vccz .LBB0_309
	s_ashr_i32 s61, s60, 31
	s_lshl_b64 s[4:5], s[60:61], 9
	v_ashrrev_i32_e32 v151, 31, v150
	s_waitcnt vmcnt(9)
	v_lshl_add_u64 v[8:9], s[4:5], 0, v[150:151]
	s_mov_b64 s[0:1], 0x200000
	v_cmp_gt_i64_e32 vcc, s[0:1], v[8:9]
	s_and_saveexec_b64 s[28:29], vcc
	s_movk_i32 s1, 0x1000
	s_cbranch_execz .LBB0_710
	s_load_dwordx2 s[4:5], s[62:63], 0x70
	v_readlane_b32 s6, v254, 20
	v_readlane_b32 s7, v254, 21
	v_readlane_b32 s8, v254, 22
	v_readlane_b32 s9, v254, 23
	v_and_b32_e32 v0, 63, v150
	v_lshlrev_b32_e32 v1, 3, v0
	v_lshlrev_b32_e32 v2, 4, v0
	v_readfirstlane_b32 s10, v150
	s_lshr_b32 s10, s10, 6
	s_lshl_b32 s11, s60, 3
	s_add_i32 s10, s10, s11
	s_mul_i32 s12, s59, 0x2800
	s_add_i32 s12, s12, 0x2400
	s_waitcnt lgkmcnt(0)
	s_add_u32 s4, s4, s12
	s_addc_u32 s5, s5, 0
	global_load_dwordx4 v[4:7], v2, s[4:5]
	v_mov_b32_e32 v8, 0xbfb8aa3b
	v_mov_b32_e32 v9, 0
	v_mov_b32_e32 v10, 1.0
	v_mov_b32_e32 v11, 0
	v_cmp_gt_u32_e32 vcc, 32, v0
	v_cndmask_b32_e32 v8, v8, v11, vcc
	v_cmp_gt_u32_e32 vcc, 16, v0
	v_mov_b32_e32 v11, 0x4038aa3b
	v_cndmask_b32_e32 v8, v8, v11, vcc
	v_mov_b32_e32 v11, 1.0
	v_cndmask_b32_e32 v9, v9, v11, vcc
	v_mov_b32_e32 v11, -2.0
	v_cndmask_b32_e32 v10, v10, v11, vcc
	s_mov_b32 s40, 0xffff0000
	s_mov_b32 s41, 0
	s_mul_i32 s11, s10, 0x1600
	s_add_u32 s30, s8, s11
	s_addc_u32 s31, s9, 0
	s_add_u32 s30, s30, 0x1200
	s_addc_u32 s31, s31, 0
	s_lshl_b32 s11, s10, 9
	s_add_u32 s36, s6, s11
	s_addc_u32 s37, s7, 0
	s_mov_b32 s38, s10
	s_and_b32 s39, s38, 0xfff
	s_cmp_lg_u32 s39, 0
	s_cselect_b32 s39, 0x1600, 0
	s_sub_u32 s34, s30, s39
	s_subb_u32 s35, s31, 0
	global_load_dwordx2 v[16:17], v1, s[30:31]
	global_load_dwordx2 v[18:19], v1, s[34:35]
	s_add_u32 s30, s30, 0xb00000
	s_addc_u32 s31, s31, 0
	s_add_i32 s38, s38, 0x800
	s_and_b32 s39, s38, 0xfff
	s_cmp_lg_u32 s39, 0
	s_cselect_b32 s39, 0x1600, 0
	s_sub_u32 s34, s30, s39
	s_subb_u32 s35, s31, 0
	global_load_dwordx2 v[20:21], v1, s[30:31]
	global_load_dwordx2 v[22:23], v1, s[34:35]
	s_add_u32 s30, s30, 0xb00000
	s_addc_u32 s31, s31, 0
	s_add_i32 s38, s38, 0x800
	s_and_b32 s39, s38, 0xfff
	s_cmp_lg_u32 s39, 0
	s_cselect_b32 s39, 0x1600, 0
	s_sub_u32 s34, s30, s39
	s_subb_u32 s35, s31, 0
	global_load_dwordx2 v[24:25], v1, s[30:31]
	global_load_dwordx2 v[26:27], v1, s[34:35]
	s_add_u32 s30, s30, 0xb00000
	s_addc_u32 s31, s31, 0
	s_add_i32 s38, s38, 0x800
	s_and_b32 s39, s38, 0xfff
	s_cmp_lg_u32 s39, 0
	s_cselect_b32 s39, 0x1600, 0
	s_sub_u32 s34, s30, s39
	s_subb_u32 s35, s31, 0
	global_load_dwordx2 v[28:29], v1, s[30:31]
	global_load_dwordx2 v[30:31], v1, s[34:35]
	s_add_u32 s30, s30, 0xb00000
	s_addc_u32 s31, s31, 0
	s_add_i32 s38, s38, 0x800
	s_and_b32 s39, s38, 0xfff
	s_cmp_lg_u32 s39, 0
	s_cselect_b32 s39, 0x1600, 0
	s_sub_u32 s34, s30, s39
	s_subb_u32 s35, s31, 0
	global_load_dwordx2 v[32:33], v1, s[30:31]
	global_load_dwordx2 v[34:35], v1, s[34:35]
	s_add_u32 s30, s30, 0xb00000
	s_addc_u32 s31, s31, 0
	s_add_i32 s38, s38, 0x800
	s_and_b32 s39, s38, 0xfff
	s_cmp_lg_u32 s39, 0
	s_cselect_b32 s39, 0x1600, 0
	s_sub_u32 s34, s30, s39
	s_subb_u32 s35, s31, 0
	global_load_dwordx2 v[36:37], v1, s[30:31]
	global_load_dwordx2 v[38:39], v1, s[34:35]
	s_add_u32 s30, s30, 0xb00000
	s_addc_u32 s31, s31, 0
	s_add_i32 s38, s38, 0x800
	s_and_b32 s39, s38, 0xfff
	s_cmp_lg_u32 s39, 0
	s_cselect_b32 s39, 0x1600, 0
	s_sub_u32 s34, s30, s39
	s_subb_u32 s35, s31, 0
	global_load_dwordx2 v[40:41], v1, s[30:31]
	global_load_dwordx2 v[42:43], v1, s[34:35]
	s_add_u32 s30, s30, 0xb00000
	s_addc_u32 s31, s31, 0
	s_add_i32 s38, s38, 0x800
	s_and_b32 s39, s38, 0xfff
	s_cmp_lg_u32 s39, 0
	s_cselect_b32 s39, 0x1600, 0
	s_sub_u32 s34, s30, s39
	s_subb_u32 s35, s31, 0
	global_load_dwordx2 v[44:45], v1, s[30:31]
	global_load_dwordx2 v[46:47], v1, s[34:35]
	s_add_u32 s30, s30, 0xb00000
	s_addc_u32 s31, s31, 0
	s_add_i32 s38, s38, 0x800
	s_and_b32 s39, s38, 0xfff
	s_cmp_lg_u32 s39, 0
	s_cselect_b32 s39, 0x1600, 0
	s_sub_u32 s34, s30, s39
	s_subb_u32 s35, s31, 0
	global_load_dwordx2 v[48:49], v1, s[30:31]
	global_load_dwordx2 v[50:51], v1, s[34:35]
	s_add_u32 s30, s30, 0xb00000
	s_addc_u32 s31, s31, 0
	s_add_i32 s38, s38, 0x800
	s_and_b32 s39, s38, 0xfff
	s_cmp_lg_u32 s39, 0
	s_cselect_b32 s39, 0x1600, 0
	s_sub_u32 s34, s30, s39
	s_subb_u32 s35, s31, 0
	global_load_dwordx2 v[52:53], v1, s[30:31]
	global_load_dwordx2 v[54:55], v1, s[34:35]
	s_add_u32 s30, s30, 0xb00000
	s_addc_u32 s31, s31, 0
	s_add_i32 s38, s38, 0x800
	s_and_b32 s39, s38, 0xfff
	s_cmp_lg_u32 s39, 0
	s_cselect_b32 s39, 0x1600, 0
	s_sub_u32 s34, s30, s39
	s_subb_u32 s35, s31, 0
	global_load_dwordx2 v[56:57], v1, s[30:31]
	global_load_dwordx2 v[58:59], v1, s[34:35]
	s_add_u32 s30, s30, 0xb00000
	s_addc_u32 s31, s31, 0
	s_add_i32 s38, s38, 0x800
	s_and_b32 s39, s38, 0xfff
	s_cmp_lg_u32 s39, 0
	s_cselect_b32 s39, 0x1600, 0
	s_sub_u32 s34, s30, s39
	s_subb_u32 s35, s31, 0
	global_load_dwordx2 v[60:61], v1, s[30:31]
	global_load_dwordx2 v[62:63], v1, s[34:35]
	s_add_u32 s30, s30, 0xb00000
	s_addc_u32 s31, s31, 0
	s_add_i32 s38, s38, 0x800
	s_and_b32 s39, s38, 0xfff
	s_cmp_lg_u32 s39, 0
	s_cselect_b32 s39, 0x1600, 0
	s_sub_u32 s34, s30, s39
	s_subb_u32 s35, s31, 0
	global_load_dwordx2 v[64:65], v1, s[30:31]
	global_load_dwordx2 v[66:67], v1, s[34:35]
	s_add_u32 s30, s30, 0xb00000
	s_addc_u32 s31, s31, 0
	s_add_i32 s38, s38, 0x800
	s_and_b32 s39, s38, 0xfff
	s_cmp_lg_u32 s39, 0
	s_cselect_b32 s39, 0x1600, 0
	s_sub_u32 s34, s30, s39
	s_subb_u32 s35, s31, 0
	global_load_dwordx2 v[68:69], v1, s[30:31]
	global_load_dwordx2 v[70:71], v1, s[34:35]
	s_add_u32 s30, s30, 0xb00000
	s_addc_u32 s31, s31, 0
	s_add_i32 s38, s38, 0x800
	s_and_b32 s39, s38, 0xfff
	s_cmp_lg_u32 s39, 0
	s_cselect_b32 s39, 0x1600, 0
	s_sub_u32 s34, s30, s39
	s_subb_u32 s35, s31, 0
	global_load_dwordx2 v[72:73], v1, s[30:31]
	global_load_dwordx2 v[74:75], v1, s[34:35]
	s_add_u32 s30, s30, 0xb00000
	s_addc_u32 s31, s31, 0
	s_add_i32 s38, s38, 0x800
	s_and_b32 s39, s38, 0xfff
	s_cmp_lg_u32 s39, 0
	s_cselect_b32 s39, 0x1600, 0
	s_sub_u32 s34, s30, s39
	s_subb_u32 s35, s31, 0
	global_load_dwordx2 v[76:77], v1, s[30:31]
	global_load_dwordx2 v[78:79], v1, s[34:35]
	s_mov_b32 s38, s10
	s_waitcnt vmcnt(30)
	s_and_b32 s39, s38, 0xfff
	s_cmp_lg_u32 s39, 0
	s_cselect_b32 s39, -1, 0
	v_and_b32_e32 v18, s39, v18
	v_and_b32_e32 v19, s39, v19
	v_lshlrev_b32_e32 v80, 16, v16
	v_and_b32_e32 v81, 0xffff0000, v16
	v_lshlrev_b32_e32 v82, 16, v17
	v_and_b32_e32 v83, 0xffff0000, v17
	v_lshlrev_b32_e32 v84, 16, v18
	v_and_b32_e32 v85, 0xffff0000, v18
	v_lshlrev_b32_e32 v86, 16, v19
	v_and_b32_e32 v87, 0xffff0000, v19
	v_sub_f32_e32 v84, v84, v80
	v_sub_f32_e32 v85, v85, v81
	v_sub_f32_e32 v86, v86, v82
	v_sub_f32_e32 v87, v87, v83
	v_fma_f32 v80, v4, v84, v80
	v_fma_f32 v81, v5, v85, v81
	v_fma_f32 v82, v6, v86, v82
	v_fma_f32 v83, v7, v87, v83
	v_mul_f32_e32 v84, v8, v80
	v_mul_f32_e32 v85, v8, v81
	v_mul_f32_e32 v86, v8, v82
	v_mul_f32_e32 v87, v8, v83
	v_exp_f32_e32 v84, v84
	v_exp_f32_e32 v85, v85
	v_exp_f32_e32 v86, v86
	v_exp_f32_e32 v87, v87
	v_add_f32_e32 v84, 1.0, v84
	v_add_f32_e32 v85, 1.0, v85
	v_add_f32_e32 v86, 1.0, v86
	v_add_f32_e32 v87, 1.0, v87
	v_rcp_f32_e32 v84, v84
	v_rcp_f32_e32 v85, v85
	v_rcp_f32_e32 v86, v86
	v_rcp_f32_e32 v87, v87
	v_fma_f32 v84, v10, v84, v9
	v_fma_f32 v85, v10, v85, v9
	v_fma_f32 v86, v10, v86, v9
	v_fma_f32 v87, v10, v87, v9
	v_cndmask_b32_e64 v80, v84, v80, s[40:41]
	v_cndmask_b32_e64 v81, v85, v81, s[40:41]
	v_cndmask_b32_e64 v82, v86, v82, s[40:41]
	v_cndmask_b32_e64 v83, v87, v83, s[40:41]
	v_cvt_pk_bf16_f32 v88, v80, v81
	v_cvt_pk_bf16_f32 v89, v82, v83
	global_store_dwordx2 v1, v[88:89], s[36:37]
	s_add_u32 s36, s36, 0x100000
	s_addc_u32 s37, s37, 0
	s_add_i32 s38, s38, 0x800
	s_waitcnt vmcnt(29)
	s_and_b32 s39, s38, 0xfff
	s_cmp_lg_u32 s39, 0
	s_cselect_b32 s39, -1, 0
	v_and_b32_e32 v22, s39, v22
	v_and_b32_e32 v23, s39, v23
	v_lshlrev_b32_e32 v80, 16, v20
	v_and_b32_e32 v81, 0xffff0000, v20
	v_lshlrev_b32_e32 v82, 16, v21
	v_and_b32_e32 v83, 0xffff0000, v21
	v_lshlrev_b32_e32 v84, 16, v22
	v_and_b32_e32 v85, 0xffff0000, v22
	v_lshlrev_b32_e32 v86, 16, v23
	v_and_b32_e32 v87, 0xffff0000, v23
	v_sub_f32_e32 v84, v84, v80
	v_sub_f32_e32 v85, v85, v81
	v_sub_f32_e32 v86, v86, v82
	v_sub_f32_e32 v87, v87, v83
	v_fma_f32 v80, v4, v84, v80
	v_fma_f32 v81, v5, v85, v81
	v_fma_f32 v82, v6, v86, v82
	v_fma_f32 v83, v7, v87, v83
	v_mul_f32_e32 v84, v8, v80
	v_mul_f32_e32 v85, v8, v81
	v_mul_f32_e32 v86, v8, v82
	v_mul_f32_e32 v87, v8, v83
	v_exp_f32_e32 v84, v84
	v_exp_f32_e32 v85, v85
	v_exp_f32_e32 v86, v86
	v_exp_f32_e32 v87, v87
	v_add_f32_e32 v84, 1.0, v84
	v_add_f32_e32 v85, 1.0, v85
	v_add_f32_e32 v86, 1.0, v86
	v_add_f32_e32 v87, 1.0, v87
	v_rcp_f32_e32 v84, v84
	v_rcp_f32_e32 v85, v85
	v_rcp_f32_e32 v86, v86
	v_rcp_f32_e32 v87, v87
	v_fma_f32 v84, v10, v84, v9
	v_fma_f32 v85, v10, v85, v9
	v_fma_f32 v86, v10, v86, v9
	v_fma_f32 v87, v10, v87, v9
	v_cndmask_b32_e64 v80, v84, v80, s[40:41]
	v_cndmask_b32_e64 v81, v85, v81, s[40:41]
	v_cndmask_b32_e64 v82, v86, v82, s[40:41]
	v_cndmask_b32_e64 v83, v87, v83, s[40:41]
	v_cvt_pk_bf16_f32 v90, v80, v81
	v_cvt_pk_bf16_f32 v91, v82, v83
	global_store_dwordx2 v1, v[90:91], s[36:37]
	s_add_u32 s36, s36, 0x100000
	s_addc_u32 s37, s37, 0
	s_add_i32 s38, s38, 0x800
	s_waitcnt vmcnt(28)
	s_and_b32 s39, s38, 0xfff
	s_cmp_lg_u32 s39, 0
	s_cselect_b32 s39, -1, 0
	v_and_b32_e32 v26, s39, v26
	v_and_b32_e32 v27, s39, v27
	v_lshlrev_b32_e32 v80, 16, v24
	v_and_b32_e32 v81, 0xffff0000, v24
	v_lshlrev_b32_e32 v82, 16, v25
	v_and_b32_e32 v83, 0xffff0000, v25
	v_lshlrev_b32_e32 v84, 16, v26
	v_and_b32_e32 v85, 0xffff0000, v26
	v_lshlrev_b32_e32 v86, 16, v27
	v_and_b32_e32 v87, 0xffff0000, v27
	v_sub_f32_e32 v84, v84, v80
	v_sub_f32_e32 v85, v85, v81
	v_sub_f32_e32 v86, v86, v82
	v_sub_f32_e32 v87, v87, v83
	v_fma_f32 v80, v4, v84, v80
	v_fma_f32 v81, v5, v85, v81
	v_fma_f32 v82, v6, v86, v82
	v_fma_f32 v83, v7, v87, v83
	v_mul_f32_e32 v84, v8, v80
	v_mul_f32_e32 v85, v8, v81
	v_mul_f32_e32 v86, v8, v82
	v_mul_f32_e32 v87, v8, v83
	v_exp_f32_e32 v84, v84
	v_exp_f32_e32 v85, v85
	v_exp_f32_e32 v86, v86
	v_exp_f32_e32 v87, v87
	v_add_f32_e32 v84, 1.0, v84
	v_add_f32_e32 v85, 1.0, v85
	v_add_f32_e32 v86, 1.0, v86
	v_add_f32_e32 v87, 1.0, v87
	v_rcp_f32_e32 v84, v84
	v_rcp_f32_e32 v85, v85
	v_rcp_f32_e32 v86, v86
	v_rcp_f32_e32 v87, v87
	v_fma_f32 v84, v10, v84, v9
	v_fma_f32 v85, v10, v85, v9
	v_fma_f32 v86, v10, v86, v9
	v_fma_f32 v87, v10, v87, v9
	v_cndmask_b32_e64 v80, v84, v80, s[40:41]
	v_cndmask_b32_e64 v81, v85, v81, s[40:41]
	v_cndmask_b32_e64 v82, v86, v82, s[40:41]
	v_cndmask_b32_e64 v83, v87, v83, s[40:41]
	v_cvt_pk_bf16_f32 v88, v80, v81
	v_cvt_pk_bf16_f32 v89, v82, v83
	global_store_dwordx2 v1, v[88:89], s[36:37]
	s_add_u32 s36, s36, 0x100000
	s_addc_u32 s37, s37, 0
	s_add_i32 s38, s38, 0x800
	s_waitcnt vmcnt(27)
	s_and_b32 s39, s38, 0xfff
	s_cmp_lg_u32 s39, 0
	s_cselect_b32 s39, -1, 0
	v_and_b32_e32 v30, s39, v30
	v_and_b32_e32 v31, s39, v31
	v_lshlrev_b32_e32 v80, 16, v28
	v_and_b32_e32 v81, 0xffff0000, v28
	v_lshlrev_b32_e32 v82, 16, v29
	v_and_b32_e32 v83, 0xffff0000, v29
	v_lshlrev_b32_e32 v84, 16, v30
	v_and_b32_e32 v85, 0xffff0000, v30
	v_lshlrev_b32_e32 v86, 16, v31
	v_and_b32_e32 v87, 0xffff0000, v31
	v_sub_f32_e32 v84, v84, v80
	v_sub_f32_e32 v85, v85, v81
	v_sub_f32_e32 v86, v86, v82
	v_sub_f32_e32 v87, v87, v83
	v_fma_f32 v80, v4, v84, v80
	v_fma_f32 v81, v5, v85, v81
	v_fma_f32 v82, v6, v86, v82
	v_fma_f32 v83, v7, v87, v83
	v_mul_f32_e32 v84, v8, v80
	v_mul_f32_e32 v85, v8, v81
	v_mul_f32_e32 v86, v8, v82
	v_mul_f32_e32 v87, v8, v83
	v_exp_f32_e32 v84, v84
	v_exp_f32_e32 v85, v85
	v_exp_f32_e32 v86, v86
	v_exp_f32_e32 v87, v87
	v_add_f32_e32 v84, 1.0, v84
	v_add_f32_e32 v85, 1.0, v85
	v_add_f32_e32 v86, 1.0, v86
	v_add_f32_e32 v87, 1.0, v87
	v_rcp_f32_e32 v84, v84
	v_rcp_f32_e32 v85, v85
	v_rcp_f32_e32 v86, v86
	v_rcp_f32_e32 v87, v87
	v_fma_f32 v84, v10, v84, v9
	v_fma_f32 v85, v10, v85, v9
	v_fma_f32 v86, v10, v86, v9
	v_fma_f32 v87, v10, v87, v9
	v_cndmask_b32_e64 v80, v84, v80, s[40:41]
	v_cndmask_b32_e64 v81, v85, v81, s[40:41]
	v_cndmask_b32_e64 v82, v86, v82, s[40:41]
	v_cndmask_b32_e64 v83, v87, v83, s[40:41]
	v_cvt_pk_bf16_f32 v90, v80, v81
	v_cvt_pk_bf16_f32 v91, v82, v83
	global_store_dwordx2 v1, v[90:91], s[36:37]
	s_add_u32 s36, s36, 0x100000
	s_addc_u32 s37, s37, 0
	s_add_i32 s38, s38, 0x800
	s_waitcnt vmcnt(26)
	s_and_b32 s39, s38, 0xfff
	s_cmp_lg_u32 s39, 0
	s_cselect_b32 s39, -1, 0
	v_and_b32_e32 v34, s39, v34
	v_and_b32_e32 v35, s39, v35
	v_lshlrev_b32_e32 v80, 16, v32
	v_and_b32_e32 v81, 0xffff0000, v32
	v_lshlrev_b32_e32 v82, 16, v33
	v_and_b32_e32 v83, 0xffff0000, v33
	v_lshlrev_b32_e32 v84, 16, v34
	v_and_b32_e32 v85, 0xffff0000, v34
	v_lshlrev_b32_e32 v86, 16, v35
	v_and_b32_e32 v87, 0xffff0000, v35
	v_sub_f32_e32 v84, v84, v80
	v_sub_f32_e32 v85, v85, v81
	v_sub_f32_e32 v86, v86, v82
	v_sub_f32_e32 v87, v87, v83
	v_fma_f32 v80, v4, v84, v80
	v_fma_f32 v81, v5, v85, v81
	v_fma_f32 v82, v6, v86, v82
	v_fma_f32 v83, v7, v87, v83
	v_mul_f32_e32 v84, v8, v80
	v_mul_f32_e32 v85, v8, v81
	v_mul_f32_e32 v86, v8, v82
	v_mul_f32_e32 v87, v8, v83
	v_exp_f32_e32 v84, v84
	v_exp_f32_e32 v85, v85
	v_exp_f32_e32 v86, v86
	v_exp_f32_e32 v87, v87
	v_add_f32_e32 v84, 1.0, v84
	v_add_f32_e32 v85, 1.0, v85
	v_add_f32_e32 v86, 1.0, v86
	v_add_f32_e32 v87, 1.0, v87
	v_rcp_f32_e32 v84, v84
	v_rcp_f32_e32 v85, v85
	v_rcp_f32_e32 v86, v86
	v_rcp_f32_e32 v87, v87
	v_fma_f32 v84, v10, v84, v9
	v_fma_f32 v85, v10, v85, v9
	v_fma_f32 v86, v10, v86, v9
	v_fma_f32 v87, v10, v87, v9
	v_cndmask_b32_e64 v80, v84, v80, s[40:41]
	v_cndmask_b32_e64 v81, v85, v81, s[40:41]
	v_cndmask_b32_e64 v82, v86, v82, s[40:41]
	v_cndmask_b32_e64 v83, v87, v83, s[40:41]
	v_cvt_pk_bf16_f32 v88, v80, v81
	v_cvt_pk_bf16_f32 v89, v82, v83
	global_store_dwordx2 v1, v[88:89], s[36:37]
	s_add_u32 s36, s36, 0x100000
	s_addc_u32 s37, s37, 0
	s_add_i32 s38, s38, 0x800
	s_waitcnt vmcnt(25)
	s_and_b32 s39, s38, 0xfff
	s_cmp_lg_u32 s39, 0
	s_cselect_b32 s39, -1, 0
	v_and_b32_e32 v38, s39, v38
	v_and_b32_e32 v39, s39, v39
	v_lshlrev_b32_e32 v80, 16, v36
	v_and_b32_e32 v81, 0xffff0000, v36
	v_lshlrev_b32_e32 v82, 16, v37
	v_and_b32_e32 v83, 0xffff0000, v37
	v_lshlrev_b32_e32 v84, 16, v38
	v_and_b32_e32 v85, 0xffff0000, v38
	v_lshlrev_b32_e32 v86, 16, v39
	v_and_b32_e32 v87, 0xffff0000, v39
	v_sub_f32_e32 v84, v84, v80
	v_sub_f32_e32 v85, v85, v81
	v_sub_f32_e32 v86, v86, v82
	v_sub_f32_e32 v87, v87, v83
	v_fma_f32 v80, v4, v84, v80
	v_fma_f32 v81, v5, v85, v81
	v_fma_f32 v82, v6, v86, v82
	v_fma_f32 v83, v7, v87, v83
	v_mul_f32_e32 v84, v8, v80
	v_mul_f32_e32 v85, v8, v81
	v_mul_f32_e32 v86, v8, v82
	v_mul_f32_e32 v87, v8, v83
	v_exp_f32_e32 v84, v84
	v_exp_f32_e32 v85, v85
	v_exp_f32_e32 v86, v86
	v_exp_f32_e32 v87, v87
	v_add_f32_e32 v84, 1.0, v84
	v_add_f32_e32 v85, 1.0, v85
	v_add_f32_e32 v86, 1.0, v86
	v_add_f32_e32 v87, 1.0, v87
	v_rcp_f32_e32 v84, v84
	v_rcp_f32_e32 v85, v85
	v_rcp_f32_e32 v86, v86
	v_rcp_f32_e32 v87, v87
	v_fma_f32 v84, v10, v84, v9
	v_fma_f32 v85, v10, v85, v9
	v_fma_f32 v86, v10, v86, v9
	v_fma_f32 v87, v10, v87, v9
	v_cndmask_b32_e64 v80, v84, v80, s[40:41]
	v_cndmask_b32_e64 v81, v85, v81, s[40:41]
	v_cndmask_b32_e64 v82, v86, v82, s[40:41]
	v_cndmask_b32_e64 v83, v87, v83, s[40:41]
	v_cvt_pk_bf16_f32 v90, v80, v81
	v_cvt_pk_bf16_f32 v91, v82, v83
	global_store_dwordx2 v1, v[90:91], s[36:37]
	s_add_u32 s36, s36, 0x100000
	s_addc_u32 s37, s37, 0
	s_add_i32 s38, s38, 0x800
	s_waitcnt vmcnt(24)
	s_and_b32 s39, s38, 0xfff
	s_cmp_lg_u32 s39, 0
	s_cselect_b32 s39, -1, 0
	v_and_b32_e32 v42, s39, v42
	v_and_b32_e32 v43, s39, v43
	v_lshlrev_b32_e32 v80, 16, v40
	v_and_b32_e32 v81, 0xffff0000, v40
	v_lshlrev_b32_e32 v82, 16, v41
	v_and_b32_e32 v83, 0xffff0000, v41
	v_lshlrev_b32_e32 v84, 16, v42
	v_and_b32_e32 v85, 0xffff0000, v42
	v_lshlrev_b32_e32 v86, 16, v43
	v_and_b32_e32 v87, 0xffff0000, v43
	v_sub_f32_e32 v84, v84, v80
	v_sub_f32_e32 v85, v85, v81
	v_sub_f32_e32 v86, v86, v82
	v_sub_f32_e32 v87, v87, v83
	v_fma_f32 v80, v4, v84, v80
	v_fma_f32 v81, v5, v85, v81
	v_fma_f32 v82, v6, v86, v82
	v_fma_f32 v83, v7, v87, v83
	v_mul_f32_e32 v84, v8, v80
	v_mul_f32_e32 v85, v8, v81
	v_mul_f32_e32 v86, v8, v82
	v_mul_f32_e32 v87, v8, v83
	v_exp_f32_e32 v84, v84
	v_exp_f32_e32 v85, v85
	v_exp_f32_e32 v86, v86
	v_exp_f32_e32 v87, v87
	v_add_f32_e32 v84, 1.0, v84
	v_add_f32_e32 v85, 1.0, v85
	v_add_f32_e32 v86, 1.0, v86
	v_add_f32_e32 v87, 1.0, v87
	v_rcp_f32_e32 v84, v84
	v_rcp_f32_e32 v85, v85
	v_rcp_f32_e32 v86, v86
	v_rcp_f32_e32 v87, v87
	v_fma_f32 v84, v10, v84, v9
	v_fma_f32 v85, v10, v85, v9
	v_fma_f32 v86, v10, v86, v9
	v_fma_f32 v87, v10, v87, v9
	v_cndmask_b32_e64 v80, v84, v80, s[40:41]
	v_cndmask_b32_e64 v81, v85, v81, s[40:41]
	v_cndmask_b32_e64 v82, v86, v82, s[40:41]
	v_cndmask_b32_e64 v83, v87, v83, s[40:41]
	v_cvt_pk_bf16_f32 v88, v80, v81
	v_cvt_pk_bf16_f32 v89, v82, v83
	global_store_dwordx2 v1, v[88:89], s[36:37]
	s_add_u32 s36, s36, 0x100000
	s_addc_u32 s37, s37, 0
	s_add_i32 s38, s38, 0x800
	s_waitcnt vmcnt(23)
	s_and_b32 s39, s38, 0xfff
	s_cmp_lg_u32 s39, 0
	s_cselect_b32 s39, -1, 0
	v_and_b32_e32 v46, s39, v46
	v_and_b32_e32 v47, s39, v47
	v_lshlrev_b32_e32 v80, 16, v44
	v_and_b32_e32 v81, 0xffff0000, v44
	v_lshlrev_b32_e32 v82, 16, v45
	v_and_b32_e32 v83, 0xffff0000, v45
	v_lshlrev_b32_e32 v84, 16, v46
	v_and_b32_e32 v85, 0xffff0000, v46
	v_lshlrev_b32_e32 v86, 16, v47
	v_and_b32_e32 v87, 0xffff0000, v47
	v_sub_f32_e32 v84, v84, v80
	v_sub_f32_e32 v85, v85, v81
	v_sub_f32_e32 v86, v86, v82
	v_sub_f32_e32 v87, v87, v83
	v_fma_f32 v80, v4, v84, v80
	v_fma_f32 v81, v5, v85, v81
	v_fma_f32 v82, v6, v86, v82
	v_fma_f32 v83, v7, v87, v83
	v_mul_f32_e32 v84, v8, v80
	v_mul_f32_e32 v85, v8, v81
	v_mul_f32_e32 v86, v8, v82
	v_mul_f32_e32 v87, v8, v83
	v_exp_f32_e32 v84, v84
	v_exp_f32_e32 v85, v85
	v_exp_f32_e32 v86, v86
	v_exp_f32_e32 v87, v87
	v_add_f32_e32 v84, 1.0, v84
	v_add_f32_e32 v85, 1.0, v85
	v_add_f32_e32 v86, 1.0, v86
	v_add_f32_e32 v87, 1.0, v87
	v_rcp_f32_e32 v84, v84
	v_rcp_f32_e32 v85, v85
	v_rcp_f32_e32 v86, v86
	v_rcp_f32_e32 v87, v87
	v_fma_f32 v84, v10, v84, v9
	v_fma_f32 v85, v10, v85, v9
	v_fma_f32 v86, v10, v86, v9
	v_fma_f32 v87, v10, v87, v9
	v_cndmask_b32_e64 v80, v84, v80, s[40:41]
	v_cndmask_b32_e64 v81, v85, v81, s[40:41]
	v_cndmask_b32_e64 v82, v86, v82, s[40:41]
	v_cndmask_b32_e64 v83, v87, v83, s[40:41]
	v_cvt_pk_bf16_f32 v90, v80, v81
	v_cvt_pk_bf16_f32 v91, v82, v83
	global_store_dwordx2 v1, v[90:91], s[36:37]
	s_add_u32 s36, s36, 0x100000
	s_addc_u32 s37, s37, 0
	s_add_i32 s38, s38, 0x800
	s_waitcnt vmcnt(22)
	s_and_b32 s39, s38, 0xfff
	s_cmp_lg_u32 s39, 0
	s_cselect_b32 s39, -1, 0
	v_and_b32_e32 v50, s39, v50
	v_and_b32_e32 v51, s39, v51
	v_lshlrev_b32_e32 v80, 16, v48
	v_and_b32_e32 v81, 0xffff0000, v48
	v_lshlrev_b32_e32 v82, 16, v49
	v_and_b32_e32 v83, 0xffff0000, v49
	v_lshlrev_b32_e32 v84, 16, v50
	v_and_b32_e32 v85, 0xffff0000, v50
	v_lshlrev_b32_e32 v86, 16, v51
	v_and_b32_e32 v87, 0xffff0000, v51
	v_sub_f32_e32 v84, v84, v80
	v_sub_f32_e32 v85, v85, v81
	v_sub_f32_e32 v86, v86, v82
	v_sub_f32_e32 v87, v87, v83
	v_fma_f32 v80, v4, v84, v80
	v_fma_f32 v81, v5, v85, v81
	v_fma_f32 v82, v6, v86, v82
	v_fma_f32 v83, v7, v87, v83
	v_mul_f32_e32 v84, v8, v80
	v_mul_f32_e32 v85, v8, v81
	v_mul_f32_e32 v86, v8, v82
	v_mul_f32_e32 v87, v8, v83
	v_exp_f32_e32 v84, v84
	v_exp_f32_e32 v85, v85
	v_exp_f32_e32 v86, v86
	v_exp_f32_e32 v87, v87
	v_add_f32_e32 v84, 1.0, v84
	v_add_f32_e32 v85, 1.0, v85
	v_add_f32_e32 v86, 1.0, v86
	v_add_f32_e32 v87, 1.0, v87
	v_rcp_f32_e32 v84, v84
	v_rcp_f32_e32 v85, v85
	v_rcp_f32_e32 v86, v86
	v_rcp_f32_e32 v87, v87
	v_fma_f32 v84, v10, v84, v9
	v_fma_f32 v85, v10, v85, v9
	v_fma_f32 v86, v10, v86, v9
	v_fma_f32 v87, v10, v87, v9
	v_cndmask_b32_e64 v80, v84, v80, s[40:41]
	v_cndmask_b32_e64 v81, v85, v81, s[40:41]
	v_cndmask_b32_e64 v82, v86, v82, s[40:41]
	v_cndmask_b32_e64 v83, v87, v83, s[40:41]
	v_cvt_pk_bf16_f32 v88, v80, v81
	v_cvt_pk_bf16_f32 v89, v82, v83
	global_store_dwordx2 v1, v[88:89], s[36:37]
	s_add_u32 s36, s36, 0x100000
	s_addc_u32 s37, s37, 0
	s_add_i32 s38, s38, 0x800
	s_waitcnt vmcnt(21)
	s_and_b32 s39, s38, 0xfff
	s_cmp_lg_u32 s39, 0
	s_cselect_b32 s39, -1, 0
	v_and_b32_e32 v54, s39, v54
	v_and_b32_e32 v55, s39, v55
	v_lshlrev_b32_e32 v80, 16, v52
	v_and_b32_e32 v81, 0xffff0000, v52
	v_lshlrev_b32_e32 v82, 16, v53
	v_and_b32_e32 v83, 0xffff0000, v53
	v_lshlrev_b32_e32 v84, 16, v54
	v_and_b32_e32 v85, 0xffff0000, v54
	v_lshlrev_b32_e32 v86, 16, v55
	v_and_b32_e32 v87, 0xffff0000, v55
	v_sub_f32_e32 v84, v84, v80
	v_sub_f32_e32 v85, v85, v81
	v_sub_f32_e32 v86, v86, v82
	v_sub_f32_e32 v87, v87, v83
	v_fma_f32 v80, v4, v84, v80
	v_fma_f32 v81, v5, v85, v81
	v_fma_f32 v82, v6, v86, v82
	v_fma_f32 v83, v7, v87, v83
	v_mul_f32_e32 v84, v8, v80
	v_mul_f32_e32 v85, v8, v81
	v_mul_f32_e32 v86, v8, v82
	v_mul_f32_e32 v87, v8, v83
	v_exp_f32_e32 v84, v84
	v_exp_f32_e32 v85, v85
	v_exp_f32_e32 v86, v86
	v_exp_f32_e32 v87, v87
	v_add_f32_e32 v84, 1.0, v84
	v_add_f32_e32 v85, 1.0, v85
	v_add_f32_e32 v86, 1.0, v86
	v_add_f32_e32 v87, 1.0, v87
	v_rcp_f32_e32 v84, v84
	v_rcp_f32_e32 v85, v85
	v_rcp_f32_e32 v86, v86
	v_rcp_f32_e32 v87, v87
	v_fma_f32 v84, v10, v84, v9
	v_fma_f32 v85, v10, v85, v9
	v_fma_f32 v86, v10, v86, v9
	v_fma_f32 v87, v10, v87, v9
	v_cndmask_b32_e64 v80, v84, v80, s[40:41]
	v_cndmask_b32_e64 v81, v85, v81, s[40:41]
	v_cndmask_b32_e64 v82, v86, v82, s[40:41]
	v_cndmask_b32_e64 v83, v87, v83, s[40:41]
	v_cvt_pk_bf16_f32 v90, v80, v81
	v_cvt_pk_bf16_f32 v91, v82, v83
	global_store_dwordx2 v1, v[90:91], s[36:37]
	s_add_u32 s36, s36, 0x100000
	s_addc_u32 s37, s37, 0
	s_add_i32 s38, s38, 0x800
	s_waitcnt vmcnt(20)
	s_and_b32 s39, s38, 0xfff
	s_cmp_lg_u32 s39, 0
	s_cselect_b32 s39, -1, 0
	v_and_b32_e32 v58, s39, v58
	v_and_b32_e32 v59, s39, v59
	v_lshlrev_b32_e32 v80, 16, v56
	v_and_b32_e32 v81, 0xffff0000, v56
	v_lshlrev_b32_e32 v82, 16, v57
	v_and_b32_e32 v83, 0xffff0000, v57
	v_lshlrev_b32_e32 v84, 16, v58
	v_and_b32_e32 v85, 0xffff0000, v58
	v_lshlrev_b32_e32 v86, 16, v59
	v_and_b32_e32 v87, 0xffff0000, v59
	v_sub_f32_e32 v84, v84, v80
	v_sub_f32_e32 v85, v85, v81
	v_sub_f32_e32 v86, v86, v82
	v_sub_f32_e32 v87, v87, v83
	v_fma_f32 v80, v4, v84, v80
	v_fma_f32 v81, v5, v85, v81
	v_fma_f32 v82, v6, v86, v82
	v_fma_f32 v83, v7, v87, v83
	v_mul_f32_e32 v84, v8, v80
	v_mul_f32_e32 v85, v8, v81
	v_mul_f32_e32 v86, v8, v82
	v_mul_f32_e32 v87, v8, v83
	v_exp_f32_e32 v84, v84
	v_exp_f32_e32 v85, v85
	v_exp_f32_e32 v86, v86
	v_exp_f32_e32 v87, v87
	v_add_f32_e32 v84, 1.0, v84
	v_add_f32_e32 v85, 1.0, v85
	v_add_f32_e32 v86, 1.0, v86
	v_add_f32_e32 v87, 1.0, v87
	v_rcp_f32_e32 v84, v84
	v_rcp_f32_e32 v85, v85
	v_rcp_f32_e32 v86, v86
	v_rcp_f32_e32 v87, v87
	v_fma_f32 v84, v10, v84, v9
	v_fma_f32 v85, v10, v85, v9
	v_fma_f32 v86, v10, v86, v9
	v_fma_f32 v87, v10, v87, v9
	v_cndmask_b32_e64 v80, v84, v80, s[40:41]
	v_cndmask_b32_e64 v81, v85, v81, s[40:41]
	v_cndmask_b32_e64 v82, v86, v82, s[40:41]
	v_cndmask_b32_e64 v83, v87, v83, s[40:41]
	v_cvt_pk_bf16_f32 v88, v80, v81
	v_cvt_pk_bf16_f32 v89, v82, v83
	global_store_dwordx2 v1, v[88:89], s[36:37]
	s_add_u32 s36, s36, 0x100000
	s_addc_u32 s37, s37, 0
	s_add_i32 s38, s38, 0x800
	s_waitcnt vmcnt(19)
	s_and_b32 s39, s38, 0xfff
	s_cmp_lg_u32 s39, 0
	s_cselect_b32 s39, -1, 0
	v_and_b32_e32 v62, s39, v62
	v_and_b32_e32 v63, s39, v63
	v_lshlrev_b32_e32 v80, 16, v60
	v_and_b32_e32 v81, 0xffff0000, v60
	v_lshlrev_b32_e32 v82, 16, v61
	v_and_b32_e32 v83, 0xffff0000, v61
	v_lshlrev_b32_e32 v84, 16, v62
	v_and_b32_e32 v85, 0xffff0000, v62
	v_lshlrev_b32_e32 v86, 16, v63
	v_and_b32_e32 v87, 0xffff0000, v63
	v_sub_f32_e32 v84, v84, v80
	v_sub_f32_e32 v85, v85, v81
	v_sub_f32_e32 v86, v86, v82
	v_sub_f32_e32 v87, v87, v83
	v_fma_f32 v80, v4, v84, v80
	v_fma_f32 v81, v5, v85, v81
	v_fma_f32 v82, v6, v86, v82
	v_fma_f32 v83, v7, v87, v83
	v_mul_f32_e32 v84, v8, v80
	v_mul_f32_e32 v85, v8, v81
	v_mul_f32_e32 v86, v8, v82
	v_mul_f32_e32 v87, v8, v83
	v_exp_f32_e32 v84, v84
	v_exp_f32_e32 v85, v85
	v_exp_f32_e32 v86, v86
	v_exp_f32_e32 v87, v87
	v_add_f32_e32 v84, 1.0, v84
	v_add_f32_e32 v85, 1.0, v85
	v_add_f32_e32 v86, 1.0, v86
	v_add_f32_e32 v87, 1.0, v87
	v_rcp_f32_e32 v84, v84
	v_rcp_f32_e32 v85, v85
	v_rcp_f32_e32 v86, v86
	v_rcp_f32_e32 v87, v87
	v_fma_f32 v84, v10, v84, v9
	v_fma_f32 v85, v10, v85, v9
	v_fma_f32 v86, v10, v86, v9
	v_fma_f32 v87, v10, v87, v9
	v_cndmask_b32_e64 v80, v84, v80, s[40:41]
	v_cndmask_b32_e64 v81, v85, v81, s[40:41]
	v_cndmask_b32_e64 v82, v86, v82, s[40:41]
	v_cndmask_b32_e64 v83, v87, v83, s[40:41]
	v_cvt_pk_bf16_f32 v90, v80, v81
	v_cvt_pk_bf16_f32 v91, v82, v83
	global_store_dwordx2 v1, v[90:91], s[36:37]
	s_add_u32 s36, s36, 0x100000
	s_addc_u32 s37, s37, 0
	s_add_i32 s38, s38, 0x800
	s_waitcnt vmcnt(18)
	s_and_b32 s39, s38, 0xfff
	s_cmp_lg_u32 s39, 0
	s_cselect_b32 s39, -1, 0
	v_and_b32_e32 v66, s39, v66
	v_and_b32_e32 v67, s39, v67
	v_lshlrev_b32_e32 v80, 16, v64
	v_and_b32_e32 v81, 0xffff0000, v64
	v_lshlrev_b32_e32 v82, 16, v65
	v_and_b32_e32 v83, 0xffff0000, v65
	v_lshlrev_b32_e32 v84, 16, v66
	v_and_b32_e32 v85, 0xffff0000, v66
	v_lshlrev_b32_e32 v86, 16, v67
	v_and_b32_e32 v87, 0xffff0000, v67
	v_sub_f32_e32 v84, v84, v80
	v_sub_f32_e32 v85, v85, v81
	v_sub_f32_e32 v86, v86, v82
	v_sub_f32_e32 v87, v87, v83
	v_fma_f32 v80, v4, v84, v80
	v_fma_f32 v81, v5, v85, v81
	v_fma_f32 v82, v6, v86, v82
	v_fma_f32 v83, v7, v87, v83
	v_mul_f32_e32 v84, v8, v80
	v_mul_f32_e32 v85, v8, v81
	v_mul_f32_e32 v86, v8, v82
	v_mul_f32_e32 v87, v8, v83
	v_exp_f32_e32 v84, v84
	v_exp_f32_e32 v85, v85
	v_exp_f32_e32 v86, v86
	v_exp_f32_e32 v87, v87
	v_add_f32_e32 v84, 1.0, v84
	v_add_f32_e32 v85, 1.0, v85
	v_add_f32_e32 v86, 1.0, v86
	v_add_f32_e32 v87, 1.0, v87
	v_rcp_f32_e32 v84, v84
	v_rcp_f32_e32 v85, v85
	v_rcp_f32_e32 v86, v86
	v_rcp_f32_e32 v87, v87
	v_fma_f32 v84, v10, v84, v9
	v_fma_f32 v85, v10, v85, v9
	v_fma_f32 v86, v10, v86, v9
	v_fma_f32 v87, v10, v87, v9
	v_cndmask_b32_e64 v80, v84, v80, s[40:41]
	v_cndmask_b32_e64 v81, v85, v81, s[40:41]
	v_cndmask_b32_e64 v82, v86, v82, s[40:41]
	v_cndmask_b32_e64 v83, v87, v83, s[40:41]
	v_cvt_pk_bf16_f32 v88, v80, v81
	v_cvt_pk_bf16_f32 v89, v82, v83
	global_store_dwordx2 v1, v[88:89], s[36:37]
	s_add_u32 s36, s36, 0x100000
	s_addc_u32 s37, s37, 0
	s_add_i32 s38, s38, 0x800
	s_waitcnt vmcnt(17)
	s_and_b32 s39, s38, 0xfff
	s_cmp_lg_u32 s39, 0
	s_cselect_b32 s39, -1, 0
	v_and_b32_e32 v70, s39, v70
	v_and_b32_e32 v71, s39, v71
	v_lshlrev_b32_e32 v80, 16, v68
	v_and_b32_e32 v81, 0xffff0000, v68
	v_lshlrev_b32_e32 v82, 16, v69
	v_and_b32_e32 v83, 0xffff0000, v69
	v_lshlrev_b32_e32 v84, 16, v70
	v_and_b32_e32 v85, 0xffff0000, v70
	v_lshlrev_b32_e32 v86, 16, v71
	v_and_b32_e32 v87, 0xffff0000, v71
	v_sub_f32_e32 v84, v84, v80
	v_sub_f32_e32 v85, v85, v81
	v_sub_f32_e32 v86, v86, v82
	v_sub_f32_e32 v87, v87, v83
	v_fma_f32 v80, v4, v84, v80
	v_fma_f32 v81, v5, v85, v81
	v_fma_f32 v82, v6, v86, v82
	v_fma_f32 v83, v7, v87, v83
	v_mul_f32_e32 v84, v8, v80
	v_mul_f32_e32 v85, v8, v81
	v_mul_f32_e32 v86, v8, v82
	v_mul_f32_e32 v87, v8, v83
	v_exp_f32_e32 v84, v84
	v_exp_f32_e32 v85, v85
	v_exp_f32_e32 v86, v86
	v_exp_f32_e32 v87, v87
	v_add_f32_e32 v84, 1.0, v84
	v_add_f32_e32 v85, 1.0, v85
	v_add_f32_e32 v86, 1.0, v86
	v_add_f32_e32 v87, 1.0, v87
	v_rcp_f32_e32 v84, v84
	v_rcp_f32_e32 v85, v85
	v_rcp_f32_e32 v86, v86
	v_rcp_f32_e32 v87, v87
	v_fma_f32 v84, v10, v84, v9
	v_fma_f32 v85, v10, v85, v9
	v_fma_f32 v86, v10, v86, v9
	v_fma_f32 v87, v10, v87, v9
	v_cndmask_b32_e64 v80, v84, v80, s[40:41]
	v_cndmask_b32_e64 v81, v85, v81, s[40:41]
	v_cndmask_b32_e64 v82, v86, v82, s[40:41]
	v_cndmask_b32_e64 v83, v87, v83, s[40:41]
	v_cvt_pk_bf16_f32 v90, v80, v81
	v_cvt_pk_bf16_f32 v91, v82, v83
	global_store_dwordx2 v1, v[90:91], s[36:37]
	s_add_u32 s36, s36, 0x100000
	s_addc_u32 s37, s37, 0
	s_add_i32 s38, s38, 0x800
	s_waitcnt vmcnt(16)
	s_and_b32 s39, s38, 0xfff
	s_cmp_lg_u32 s39, 0
	s_cselect_b32 s39, -1, 0
	v_and_b32_e32 v74, s39, v74
	v_and_b32_e32 v75, s39, v75
	v_lshlrev_b32_e32 v80, 16, v72
	v_and_b32_e32 v81, 0xffff0000, v72
	v_lshlrev_b32_e32 v82, 16, v73
	v_and_b32_e32 v83, 0xffff0000, v73
	v_lshlrev_b32_e32 v84, 16, v74
	v_and_b32_e32 v85, 0xffff0000, v74
	v_lshlrev_b32_e32 v86, 16, v75
	v_and_b32_e32 v87, 0xffff0000, v75
	v_sub_f32_e32 v84, v84, v80
	v_sub_f32_e32 v85, v85, v81
	v_sub_f32_e32 v86, v86, v82
	v_sub_f32_e32 v87, v87, v83
	v_fma_f32 v80, v4, v84, v80
	v_fma_f32 v81, v5, v85, v81
	v_fma_f32 v82, v6, v86, v82
	v_fma_f32 v83, v7, v87, v83
	v_mul_f32_e32 v84, v8, v80
	v_mul_f32_e32 v85, v8, v81
	v_mul_f32_e32 v86, v8, v82
	v_mul_f32_e32 v87, v8, v83
	v_exp_f32_e32 v84, v84
	v_exp_f32_e32 v85, v85
	v_exp_f32_e32 v86, v86
	v_exp_f32_e32 v87, v87
	v_add_f32_e32 v84, 1.0, v84
	v_add_f32_e32 v85, 1.0, v85
	v_add_f32_e32 v86, 1.0, v86
	v_add_f32_e32 v87, 1.0, v87
	v_rcp_f32_e32 v84, v84
	v_rcp_f32_e32 v85, v85
	v_rcp_f32_e32 v86, v86
	v_rcp_f32_e32 v87, v87
	v_fma_f32 v84, v10, v84, v9
	v_fma_f32 v85, v10, v85, v9
	v_fma_f32 v86, v10, v86, v9
	v_fma_f32 v87, v10, v87, v9
	v_cndmask_b32_e64 v80, v84, v80, s[40:41]
	v_cndmask_b32_e64 v81, v85, v81, s[40:41]
	v_cndmask_b32_e64 v82, v86, v82, s[40:41]
	v_cndmask_b32_e64 v83, v87, v83, s[40:41]
	v_cvt_pk_bf16_f32 v88, v80, v81
	v_cvt_pk_bf16_f32 v89, v82, v83
	global_store_dwordx2 v1, v[88:89], s[36:37]
	s_add_u32 s36, s36, 0x100000
	s_addc_u32 s37, s37, 0
	s_add_i32 s38, s38, 0x800
	s_waitcnt vmcnt(15)
	s_and_b32 s39, s38, 0xfff
	s_cmp_lg_u32 s39, 0
	s_cselect_b32 s39, -1, 0
	v_and_b32_e32 v78, s39, v78
	v_and_b32_e32 v79, s39, v79
	v_lshlrev_b32_e32 v80, 16, v76
	v_and_b32_e32 v81, 0xffff0000, v76
	v_lshlrev_b32_e32 v82, 16, v77
	v_and_b32_e32 v83, 0xffff0000, v77
	v_lshlrev_b32_e32 v84, 16, v78
	v_and_b32_e32 v85, 0xffff0000, v78
	v_lshlrev_b32_e32 v86, 16, v79
	v_and_b32_e32 v87, 0xffff0000, v79
	v_sub_f32_e32 v84, v84, v80
	v_sub_f32_e32 v85, v85, v81
	v_sub_f32_e32 v86, v86, v82
	v_sub_f32_e32 v87, v87, v83
	v_fma_f32 v80, v4, v84, v80
	v_fma_f32 v81, v5, v85, v81
	v_fma_f32 v82, v6, v86, v82
	v_fma_f32 v83, v7, v87, v83
	v_mul_f32_e32 v84, v8, v80
	v_mul_f32_e32 v85, v8, v81
	v_mul_f32_e32 v86, v8, v82
	v_mul_f32_e32 v87, v8, v83
	v_exp_f32_e32 v84, v84
	v_exp_f32_e32 v85, v85
	v_exp_f32_e32 v86, v86
	v_exp_f32_e32 v87, v87
	v_add_f32_e32 v84, 1.0, v84
	v_add_f32_e32 v85, 1.0, v85
	v_add_f32_e32 v86, 1.0, v86
	v_add_f32_e32 v87, 1.0, v87
	v_rcp_f32_e32 v84, v84
	v_rcp_f32_e32 v85, v85
	v_rcp_f32_e32 v86, v86
	v_rcp_f32_e32 v87, v87
	v_fma_f32 v84, v10, v84, v9
	v_fma_f32 v85, v10, v85, v9
	v_fma_f32 v86, v10, v86, v9
	v_fma_f32 v87, v10, v87, v9
	v_cndmask_b32_e64 v80, v84, v80, s[40:41]
	v_cndmask_b32_e64 v81, v85, v81, s[40:41]
	v_cndmask_b32_e64 v82, v86, v82, s[40:41]
	v_cndmask_b32_e64 v83, v87, v83, s[40:41]
	v_cvt_pk_bf16_f32 v90, v80, v81
	v_cvt_pk_bf16_f32 v91, v82, v83
	global_store_dwordx2 v1, v[90:91], s[36:37]
	s_branch .LBB0_710
